# FFN-up GEMM K-loop: per-section priority flips deleted
# baseline (speedup 1.0000x reference)
; #define PG8_STAGE(bufoff, gbase, voff) do { _Pragma("unroll") for (int _i = 0; _i < 2; ++_i) \
;         __builtin_amdgcn_global_load_lds((const unsigned*)((const char*)(gbase) + (voff)[_i]), (LAS unsigned*)(lds + (bufoff) + ldsw + _i * 8192), 16, 0, 0); } while (0)
; #define PG8_LDA(dst, b, h) do { _Pragma("unroll") for (int m = 0; m < 4; ++m) _Pragma("unroll") for (int k = 0; k < 2; ++k) dst[m][k] = *(const LAS bf16x8*)(lds + PG8_SA(b, h) + aoff + m * 2048 + k * 1024); } while (0)
; #define PG8_LDB(dst, b, h) do { _Pragma("unroll") for (int n = 0; n < 2; ++n) _Pragma("unroll") for (int k = 0; k < 2; ++k) dst[n][k] = *(const LAS bf16x8*)(lds + PG8_SB(b, h) + boff + n * 2048 + k * 1024); } while (0)
; #define PG8_MMA(ai, bj, At, Bt) do { __builtin_amdgcn_s_setprio(1); _Pragma("unroll") for (int m = 0; m < 4; ++m) _Pragma("unroll") for (int n = 0; n < 2; ++n) _Pragma("unroll") for (int k = 0; k < 2; ++k) \
;         acc[ai][bj][m][n] = __builtin_amdgcn_mfma_f32_16x16x32_bf16(Bt[n][k], At[m][k], acc[ai][bj][m][n], 0, 0, 0); __builtin_amdgcn_s_setprio(0); } while (0)
; #define PG8_WAIT_V(n) asm volatile("s_waitcnt vmcnt(" #n ")" ::: "memory")
; #define PG8_WAIT_L(n) asm volatile("s_waitcnt lgkmcnt(" #n ")" ::: "memory")
; #define PG8_BAR __builtin_amdgcn_s_barrier()
; #define PG8_SCHED __builtin_amdgcn_sched_barrier(0)
; template <class Epi, class Sched>
; __device__ __forceinline__ void gemm_phase(LAS unsigned char* lds, const Gemm g, const Sched& S, const Epi& E, int wv) {
;     ...
;         for (int t = 0; t < nt; t += 2) {
;             const bool last = (t == nt - 2);
;             const char* a1 = cA + (size_t)(t + 1) * kstep;
;             const char* a2 = last ? nA : cA + (size_t)(t + 2) * kstep; const char* b2 = last ? nB : cB + (size_t)(t + 2) * kstep;
;             const char* a3 = a2 + kstep; const char* b3 = b2 + kstep;
;             PG8_LDB(B0, 0, 0); PG8_LDB(B1, 0, 1); PG8_SCHED; PG8_LDA(At, 0, 0); PG8_STAGE(PG8_SA(1, 1), a1 + hstepA, voffA);
;             PG8_WAIT_V(8); PG8_WAIT_L(0); PG8_BAR; PG8_MMA(0, 0, At, B0); PG8_MMA(0, 1, At, B1); PG8_BAR; PG8_SCHED;
;             PG8_LDA(At, 0, 1); PG8_STAGE(PG8_SB(0, 0), b2, voffB); PG8_STAGE(PG8_SB(0, 1), b2 + hstepB, voffB); PG8_STAGE(PG8_SA(0, 0), a2, voffA);
;             PG8_WAIT_V(8); PG8_WAIT_L(0); PG8_BAR; PG8_MMA(1, 0, At, B0); PG8_MMA(1, 1, At, B1); PG8_BAR; PG8_SCHED;
.LBB0_201:
	s_add_u32 s0, s76, 0xfffc0080
	s_addc_u32 s1, s77, -1
	s_add_i32 s20, 0, 0x10000
	s_cmp_eq_u32 s56, 12
	s_cselect_b32 s81, s10, s1
	s_cselect_b32 s80, s11, s0
	v_add_u32_e32 v0, s20, v161
	s_cselect_b32 s79, s21, s35
	s_cselect_b32 s78, s31, s34
	s_add_i32 s26, 0, 0x14000
	ds_read_b128 v[142:145], v0
	ds_read_b128 v[146:149], v0 offset:1024
	ds_read_b128 v[150:153], v0 offset:2048
	ds_read_b128 v[154:157], v0 offset:3072
	v_add_u32_e32 v0, s26, v161
	ds_read_b128 v[162:165], v0
	ds_read_b128 v[166:169], v0 offset:1024
	ds_read_b128 v[170:173], v0 offset:2048
	ds_read_b128 v[176:179], v0 offset:3072
	v_lshl_add_u64 v[158:159], s[76:77], 0, v[138:139]
	s_add_i32 m0, s82, 0xc000
	ds_read_b128 v[180:183], v175
	ds_read_b128 v[184:187], v175 offset:1024
	ds_read_b128 v[188:191], v175 offset:2048
	ds_read_b128 v[196:199], v175 offset:3072
	ds_read_b128 v[200:203], v175 offset:4096
	ds_read_b128 v[204:207], v175 offset:5120
	ds_read_b128 v[208:211], v175 offset:6144
	ds_read_b128 v[212:215], v175 offset:7168
	global_load_lds_dwordx4 v[158:159], off
	v_lshl_add_u64 v[158:159], s[76:77], 0, v[140:141]
	s_add_i32 m0, s82, 0xe000
	s_nop 0
	global_load_lds_dwordx4 v[158:159], off
	s_waitcnt vmcnt(8)
	s_waitcnt lgkmcnt(0)
	s_barrier
	v_mfma_f32_16x16x32_bf16 v[126:129], v[142:145], v[180:183], v[126:129]
	v_mfma_f32_16x16x32_bf16 v[122:125], v[150:153], v[180:183], v[122:125]
	v_mfma_f32_16x16x32_bf16 v[118:121], v[142:145], v[188:191], v[118:121]
	v_mfma_f32_16x16x32_bf16 v[114:117], v[150:153], v[188:191], v[114:117]
	v_mfma_f32_16x16x32_bf16 v[102:105], v[142:145], v[200:203], v[102:105]
	v_mfma_f32_16x16x32_bf16 v[98:101], v[150:153], v[200:203], v[98:101]
	v_mfma_f32_16x16x32_bf16 v[86:89], v[142:145], v[208:211], v[86:89]
	v_mfma_f32_16x16x32_bf16 v[82:85], v[150:153], v[208:211], v[82:85]
	v_mfma_f32_16x16x32_bf16 v[126:129], v[146:149], v[184:187], v[126:129]
	v_mfma_f32_16x16x32_bf16 v[122:125], v[154:157], v[184:187], v[122:125]
	v_mfma_f32_16x16x32_bf16 v[118:121], v[146:149], v[196:199], v[118:121]
	v_mfma_f32_16x16x32_bf16 v[114:117], v[154:157], v[196:199], v[114:117]
	v_mfma_f32_16x16x32_bf16 v[102:105], v[146:149], v[204:207], v[102:105]
	v_mfma_f32_16x16x32_bf16 v[98:101], v[154:157], v[204:207], v[98:101]
	v_mfma_f32_16x16x32_bf16 v[86:89], v[146:149], v[212:215], v[86:89]
	v_mfma_f32_16x16x32_bf16 v[82:85], v[154:157], v[212:215], v[82:85]
	v_mfma_f32_16x16x32_bf16 v[110:113], v[162:165], v[180:183], v[110:113]
	v_mfma_f32_16x16x32_bf16 v[106:109], v[170:173], v[180:183], v[106:109]
	v_mfma_f32_16x16x32_bf16 v[94:97], v[162:165], v[188:191], v[94:97]
	v_mfma_f32_16x16x32_bf16 v[90:93], v[170:173], v[188:191], v[90:93]
	v_mfma_f32_16x16x32_bf16 v[78:81], v[162:165], v[200:203], v[78:81]
	v_mfma_f32_16x16x32_bf16 v[74:77], v[170:173], v[200:203], v[74:77]
	v_mfma_f32_16x16x32_bf16 v[70:73], v[162:165], v[208:211], v[70:73]
	v_mfma_f32_16x16x32_bf16 v[66:69], v[170:173], v[208:211], v[66:69]
	v_mfma_f32_16x16x32_bf16 v[110:113], v[166:169], v[184:187], v[110:113]
	v_mfma_f32_16x16x32_bf16 v[106:109], v[176:179], v[184:187], v[106:109]
	v_mfma_f32_16x16x32_bf16 v[94:97], v[166:169], v[196:199], v[94:97]
	v_mfma_f32_16x16x32_bf16 v[90:93], v[176:179], v[196:199], v[90:93]
	v_mfma_f32_16x16x32_bf16 v[78:81], v[166:169], v[204:207], v[78:81]
	v_mfma_f32_16x16x32_bf16 v[74:77], v[176:179], v[204:207], v[74:77]
	v_mfma_f32_16x16x32_bf16 v[70:73], v[166:169], v[212:215], v[70:73]
	v_mfma_f32_16x16x32_bf16 v[66:69], v[176:179], v[212:215], v[66:69]
	s_barrier
	s_add_i32 s0, s20, s60
	v_lshl_add_u64 v[158:159], s[78:79], 0, v[134:135]
	s_mov_b32 m0, s0
	ds_read_b128 v[180:183], v175 offset:16384
	ds_read_b128 v[184:187], v175 offset:17408
	ds_read_b128 v[188:191], v175 offset:18432
	ds_read_b128 v[196:199], v175 offset:19456
	ds_read_b128 v[200:203], v175 offset:20480
	ds_read_b128 v[204:207], v175 offset:21504
	ds_read_b128 v[208:211], v175 offset:22528
	ds_read_b128 v[212:215], v175 offset:23552
	global_load_lds_dwordx4 v[158:159], off
	s_add_i32 m0, s0, 0x2000
	s_add_u32 s0, s78, 0x40000
	v_lshl_add_u64 v[192:193], s[78:79], 0, v[130:131]
	s_addc_u32 s1, s79, 0
	s_add_i32 s20, s26, s60
	global_load_lds_dwordx4 v[192:193], off
	v_lshl_add_u64 v[216:217], s[0:1], 0, v[134:135]
	s_mov_b32 m0, s20
	v_lshl_add_u64 v[218:219], s[80:81], 0, v[132:133]
	global_load_lds_dwordx4 v[216:217], off
	v_lshl_add_u64 v[216:217], s[0:1], 0, v[130:131]
	s_add_i32 m0, s20, 0x2000
	s_nop 0
	global_load_lds_dwordx4 v[216:217], off
	v_lshl_add_u64 v[216:217], s[80:81], 0, v[136:137]
	s_mov_b32 m0, s82
	s_nop 0
	global_load_lds_dwordx4 v[216:217], off
	s_mov_b32 m0, s83
	s_nop 0
	global_load_lds_dwordx4 v[218:219], off
	s_waitcnt vmcnt(8)
	s_waitcnt lgkmcnt(0)
	s_barrier
; #define PG8_STAGE(bufoff, gbase, voff) do { _Pragma("unroll") for (int _i = 0; _i < 2; ++_i) \
;         __builtin_amdgcn_global_load_lds((const unsigned*)((const char*)(gbase) + (voff)[_i]), (LAS unsigned*)(lds + (bufoff) + ldsw + _i * 8192), 16, 0, 0); } while (0)
; #define PG8_LDA(dst, b, h) do { _Pragma("unroll") for (int m = 0; m < 4; ++m) _Pragma("unroll") for (int k = 0; k < 2; ++k) dst[m][k] = *(const LAS bf16x8*)(lds + PG8_SA(b, h) + aoff + m * 2048 + k * 1024); } while (0)
; #define PG8_LDB(dst, b, h) do { _Pragma("unroll") for (int n = 0; n < 2; ++n) _Pragma("unroll") for (int k = 0; k < 2; ++k) dst[n][k] = *(const LAS bf16x8*)(lds + PG8_SB(b, h) + boff + n * 2048 + k * 1024); } while (0)
; #define PG8_MMA(ai, bj, At, Bt) do { __builtin_amdgcn_s_setprio(1); _Pragma("unroll") for (int m = 0; m < 4; ++m) _Pragma("unroll") for (int n = 0; n < 2; ++n) _Pragma("unroll") for (int k = 0; k < 2; ++k) \
;         acc[ai][bj][m][n] = __builtin_amdgcn_mfma_f32_16x16x32_bf16(Bt[n][k], At[m][k], acc[ai][bj][m][n], 0, 0, 0); __builtin_amdgcn_s_setprio(0); } while (0)
; #define PG8_WAIT_V(n) asm volatile("s_waitcnt vmcnt(" #n ")" ::: "memory")
; #define PG8_WAIT_L(n) asm volatile("s_waitcnt lgkmcnt(" #n ")" ::: "memory")
; #define PG8_BAR __builtin_amdgcn_s_barrier()
; #define PG8_SCHED __builtin_amdgcn_sched_barrier(0)
; template <class Epi, class Sched>
; __device__ __forceinline__ void gemm_phase(LAS unsigned char* lds, const Gemm g, const Sched& S, const Epi& E, int wv) {
;     ...
;             PG8_WAIT_V(8); PG8_WAIT_L(0); PG8_BAR; PG8_MMA(0, 0, At, B0); PG8_MMA(0, 1, At, B1); PG8_BAR; PG8_SCHED;
;             PG8_LDA(At, 0, 1); PG8_STAGE(PG8_SB(0, 0), b2, voffB); PG8_STAGE(PG8_SB(0, 1), b2 + hstepB, voffB); PG8_STAGE(PG8_SA(0, 0), a2, voffA);
;             PG8_WAIT_V(8); PG8_WAIT_L(0); PG8_BAR; PG8_MMA(1, 0, At, B0); PG8_MMA(1, 1, At, B1); PG8_BAR; PG8_SCHED;
;             PG8_LDB(B0, 1, 0); PG8_LDB(B1, 1, 1); PG8_SCHED; PG8_LDA(At, 1, 0); PG8_STAGE(PG8_SA(0, 1), a2 + hstepA, voffA);
;             PG8_WAIT_V(8); PG8_WAIT_L(0); PG8_BAR; PG8_MMA(0, 0, At, B0); PG8_MMA(0, 1, At, B1); PG8_BAR; PG8_SCHED;
	v_mfma_f32_16x16x32_bf16 v[62:65], v[142:145], v[180:183], v[62:65]
	v_mfma_f32_16x16x32_bf16 v[58:61], v[150:153], v[180:183], v[58:61]
	v_mfma_f32_16x16x32_bf16 v[54:57], v[142:145], v[188:191], v[54:57]
	v_mfma_f32_16x16x32_bf16 v[50:53], v[150:153], v[188:191], v[50:53]
	v_mfma_f32_16x16x32_bf16 v[38:41], v[142:145], v[200:203], v[38:41]
	v_mfma_f32_16x16x32_bf16 v[34:37], v[150:153], v[200:203], v[34:37]
	v_mfma_f32_16x16x32_bf16 v[22:25], v[142:145], v[208:211], v[22:25]
	v_mfma_f32_16x16x32_bf16 v[18:21], v[150:153], v[208:211], v[18:21]
	v_mfma_f32_16x16x32_bf16 v[62:65], v[146:149], v[184:187], v[62:65]
	v_mfma_f32_16x16x32_bf16 v[58:61], v[154:157], v[184:187], v[58:61]
	v_mfma_f32_16x16x32_bf16 v[54:57], v[146:149], v[196:199], v[54:57]
	v_mfma_f32_16x16x32_bf16 v[50:53], v[154:157], v[196:199], v[50:53]
	v_mfma_f32_16x16x32_bf16 v[38:41], v[146:149], v[204:207], v[38:41]
	v_mfma_f32_16x16x32_bf16 v[34:37], v[154:157], v[204:207], v[34:37]
	v_mfma_f32_16x16x32_bf16 v[22:25], v[146:149], v[212:215], v[22:25]
	v_mfma_f32_16x16x32_bf16 v[18:21], v[154:157], v[212:215], v[18:21]
	v_mfma_f32_16x16x32_bf16 v[46:49], v[162:165], v[180:183], v[46:49]
	v_mfma_f32_16x16x32_bf16 v[42:45], v[170:173], v[180:183], v[42:45]
	v_mfma_f32_16x16x32_bf16 v[30:33], v[162:165], v[188:191], v[30:33]
	v_mfma_f32_16x16x32_bf16 v[26:29], v[170:173], v[188:191], v[26:29]
	v_mfma_f32_16x16x32_bf16 v[14:17], v[162:165], v[200:203], v[14:17]
	v_mfma_f32_16x16x32_bf16 v[10:13], v[170:173], v[200:203], v[10:13]
	v_mfma_f32_16x16x32_bf16 v[6:9], v[162:165], v[208:211], v[6:9]
	v_mfma_f32_16x16x32_bf16 v[2:5], v[170:173], v[208:211], v[2:5]
	v_mfma_f32_16x16x32_bf16 v[46:49], v[166:169], v[184:187], v[46:49]
	v_mfma_f32_16x16x32_bf16 v[42:45], v[176:179], v[184:187], v[42:45]
	v_mfma_f32_16x16x32_bf16 v[30:33], v[166:169], v[196:199], v[30:33]
	v_mfma_f32_16x16x32_bf16 v[26:29], v[176:179], v[196:199], v[26:29]
	v_mfma_f32_16x16x32_bf16 v[14:17], v[166:169], v[204:207], v[14:17]
	v_mfma_f32_16x16x32_bf16 v[10:13], v[176:179], v[204:207], v[10:13]
	v_mfma_f32_16x16x32_bf16 v[6:9], v[166:169], v[212:215], v[6:9]
	v_mfma_f32_16x16x32_bf16 v[2:5], v[176:179], v[212:215], v[2:5]
	s_barrier
	s_add_i32 s20, 0, 0x18000
	v_add_u32_e32 v0, s20, v161
	s_add_i32 s26, 0, 0x1c000
	ds_read_b128 v[142:145], v0
	ds_read_b128 v[146:149], v0 offset:1024
	ds_read_b128 v[150:153], v0 offset:2048
	ds_read_b128 v[154:157], v0 offset:3072
	v_add_u32_e32 v0, s26, v161
	ds_read_b128 v[162:165], v0
	ds_read_b128 v[166:169], v0 offset:1024
	ds_read_b128 v[170:173], v0 offset:2048
	ds_read_b128 v[176:179], v0 offset:3072
	s_add_u32 s0, s80, 0x40000
	s_addc_u32 s1, s81, 0
	s_mov_b32 m0, s84
	v_lshl_add_u64 v[220:221], s[0:1], 0, v[136:137]
	ds_read_b128 v[180:183], v175 offset:32768
	ds_read_b128 v[184:187], v175 offset:33792
	ds_read_b128 v[188:191], v175 offset:34816
	ds_read_b128 v[196:199], v175 offset:35840
	ds_read_b128 v[200:203], v175 offset:36864
	ds_read_b128 v[204:207], v175 offset:37888
	ds_read_b128 v[208:211], v175 offset:38912
	ds_read_b128 v[212:215], v175 offset:39936
	global_load_lds_dwordx4 v[220:221], off
	v_lshl_add_u64 v[220:221], s[0:1], 0, v[132:133]
	s_mov_b32 m0, s85
	s_nop 0
	global_load_lds_dwordx4 v[220:221], off
	s_waitcnt vmcnt(8)
	s_waitcnt lgkmcnt(0)
	s_barrier
	v_mfma_f32_16x16x32_bf16 v[126:129], v[142:145], v[180:183], v[126:129]
	v_mfma_f32_16x16x32_bf16 v[122:125], v[150:153], v[180:183], v[122:125]
	v_mfma_f32_16x16x32_bf16 v[118:121], v[142:145], v[188:191], v[118:121]
	v_mfma_f32_16x16x32_bf16 v[114:117], v[150:153], v[188:191], v[114:117]
	v_mfma_f32_16x16x32_bf16 v[102:105], v[142:145], v[200:203], v[102:105]
	v_mfma_f32_16x16x32_bf16 v[98:101], v[150:153], v[200:203], v[98:101]
	v_mfma_f32_16x16x32_bf16 v[86:89], v[142:145], v[208:211], v[86:89]
	v_mfma_f32_16x16x32_bf16 v[82:85], v[150:153], v[208:211], v[82:85]
	v_mfma_f32_16x16x32_bf16 v[126:129], v[146:149], v[184:187], v[126:129]
	v_mfma_f32_16x16x32_bf16 v[122:125], v[154:157], v[184:187], v[122:125]
	v_mfma_f32_16x16x32_bf16 v[118:121], v[146:149], v[196:199], v[118:121]
	v_mfma_f32_16x16x32_bf16 v[114:117], v[154:157], v[196:199], v[114:117]
	v_mfma_f32_16x16x32_bf16 v[102:105], v[146:149], v[204:207], v[102:105]
	v_mfma_f32_16x16x32_bf16 v[98:101], v[154:157], v[204:207], v[98:101]
	v_mfma_f32_16x16x32_bf16 v[86:89], v[146:149], v[212:215], v[86:89]
	v_mfma_f32_16x16x32_bf16 v[82:85], v[154:157], v[212:215], v[82:85]
	v_mfma_f32_16x16x32_bf16 v[110:113], v[162:165], v[180:183], v[110:113]
	v_mfma_f32_16x16x32_bf16 v[106:109], v[170:173], v[180:183], v[106:109]
	v_mfma_f32_16x16x32_bf16 v[94:97], v[162:165], v[188:191], v[94:97]
	v_mfma_f32_16x16x32_bf16 v[90:93], v[170:173], v[188:191], v[90:93]
	v_mfma_f32_16x16x32_bf16 v[78:81], v[162:165], v[200:203], v[78:81]
	v_mfma_f32_16x16x32_bf16 v[74:77], v[170:173], v[200:203], v[74:77]
	v_mfma_f32_16x16x32_bf16 v[70:73], v[162:165], v[208:211], v[70:73]
	v_mfma_f32_16x16x32_bf16 v[66:69], v[170:173], v[208:211], v[66:69]
	v_mfma_f32_16x16x32_bf16 v[110:113], v[166:169], v[184:187], v[110:113]
	v_mfma_f32_16x16x32_bf16 v[106:109], v[176:179], v[184:187], v[106:109]
	v_mfma_f32_16x16x32_bf16 v[94:97], v[166:169], v[196:199], v[94:97]
	v_mfma_f32_16x16x32_bf16 v[90:93], v[176:179], v[196:199], v[90:93]
	v_mfma_f32_16x16x32_bf16 v[78:81], v[166:169], v[204:207], v[78:81]
	v_mfma_f32_16x16x32_bf16 v[74:77], v[176:179], v[204:207], v[74:77]
	v_mfma_f32_16x16x32_bf16 v[70:73], v[166:169], v[212:215], v[70:73]
	v_mfma_f32_16x16x32_bf16 v[66:69], v[176:179], v[212:215], v[66:69]
	s_barrier
; #define PG8_STAGE(bufoff, gbase, voff) do { _Pragma("unroll") for (int _i = 0; _i < 2; ++_i) \
;         __builtin_amdgcn_global_load_lds((const unsigned*)((const char*)(gbase) + (voff)[_i]), (LAS unsigned*)(lds + (bufoff) + ldsw + _i * 8192), 16, 0, 0); } while (0)
; #define PG8_LDA(dst, b, h) do { _Pragma("unroll") for (int m = 0; m < 4; ++m) _Pragma("unroll") for (int k = 0; k < 2; ++k) dst[m][k] = *(const LAS bf16x8*)(lds + PG8_SA(b, h) + aoff + m * 2048 + k * 1024); } while (0)
; #define PG8_MMA(ai, bj, At, Bt) do { __builtin_amdgcn_s_setprio(1); _Pragma("unroll") for (int m = 0; m < 4; ++m) _Pragma("unroll") for (int n = 0; n < 2; ++n) _Pragma("unroll") for (int k = 0; k < 2; ++k) \
;         acc[ai][bj][m][n] = __builtin_amdgcn_mfma_f32_16x16x32_bf16(Bt[n][k], At[m][k], acc[ai][bj][m][n], 0, 0, 0); __builtin_amdgcn_s_setprio(0); } while (0)
; #define PG8_WAIT_V(n) asm volatile("s_waitcnt vmcnt(" #n ")" ::: "memory")
; #define PG8_WAIT_L(n) asm volatile("s_waitcnt lgkmcnt(" #n ")" ::: "memory")
; #define PG8_BAR __builtin_amdgcn_s_barrier()
; #define PG8_SCHED __builtin_amdgcn_sched_barrier(0)
; template <class Epi, class Sched>
; __device__ __forceinline__ void gemm_phase(LAS unsigned char* lds, const Gemm g, const Sched& S, const Epi& E, int wv) {
;     ...
;             PG8_WAIT_V(8); PG8_WAIT_L(0); PG8_BAR; PG8_MMA(0, 0, At, B0); PG8_MMA(0, 1, At, B1); PG8_BAR; PG8_SCHED;
;             PG8_LDA(At, 1, 1); PG8_STAGE(PG8_SB(1, 0), b3, voffB); PG8_STAGE(PG8_SB(1, 1), b3 + hstepB, voffB); PG8_STAGE(PG8_SA(1, 0), a3, voffA);
;             PG8_WAIT_V(8); PG8_WAIT_L(0); PG8_BAR; PG8_MMA(1, 0, At, B0); PG8_MMA(1, 1, At, B1); PG8_BAR; PG8_SCHED;
;         }
	s_add_i32 s0, s20, s60
	v_lshl_add_u64 v[158:159], v[158:159], 0, s[24:25]
	s_mov_b32 m0, s0
	ds_read_b128 v[180:183], v175 offset:49152
	ds_read_b128 v[184:187], v175 offset:50176
	ds_read_b128 v[188:191], v175 offset:51200
	ds_read_b128 v[196:199], v175 offset:52224
	ds_read_b128 v[200:203], v175 offset:53248
	ds_read_b128 v[204:207], v175 offset:54272
	ds_read_b128 v[208:211], v175 offset:55296
	ds_read_b128 v[212:215], v175 offset:56320
	global_load_lds_dwordx4 v[158:159], off
	s_add_i32 m0, s0, 0x2000
	s_add_u32 s0, s78, 0x40080
	v_lshl_add_u64 v[158:159], v[192:193], 0, s[24:25]
	s_addc_u32 s1, s79, 0
	s_add_i32 s20, s26, s60
	global_load_lds_dwordx4 v[158:159], off
	v_lshl_add_u64 v[158:159], s[0:1], 0, v[134:135]
	s_mov_b32 m0, s20
	s_nop 0
	global_load_lds_dwordx4 v[158:159], off
	v_lshl_add_u64 v[158:159], s[0:1], 0, v[130:131]
	s_add_i32 m0, s20, 0x2000
	s_nop 0
	global_load_lds_dwordx4 v[158:159], off
	v_lshl_add_u64 v[158:159], v[216:217], 0, s[24:25]
	s_mov_b32 m0, s86
	s_nop 0
	global_load_lds_dwordx4 v[158:159], off
	v_lshl_add_u64 v[158:159], v[218:219], 0, s[24:25]
	s_mov_b32 m0, s87
	s_nop 0
	global_load_lds_dwordx4 v[158:159], off
	s_waitcnt vmcnt(8)
	s_waitcnt lgkmcnt(0)
	s_barrier
	v_mfma_f32_16x16x32_bf16 v[62:65], v[142:145], v[180:183], v[62:65]
	v_mfma_f32_16x16x32_bf16 v[58:61], v[150:153], v[180:183], v[58:61]
	v_mfma_f32_16x16x32_bf16 v[54:57], v[142:145], v[188:191], v[54:57]
	v_mfma_f32_16x16x32_bf16 v[50:53], v[150:153], v[188:191], v[50:53]
	v_mfma_f32_16x16x32_bf16 v[38:41], v[142:145], v[200:203], v[38:41]
	v_mfma_f32_16x16x32_bf16 v[34:37], v[150:153], v[200:203], v[34:37]
	v_mfma_f32_16x16x32_bf16 v[22:25], v[142:145], v[208:211], v[22:25]
	v_mfma_f32_16x16x32_bf16 v[18:21], v[150:153], v[208:211], v[18:21]
	v_mfma_f32_16x16x32_bf16 v[62:65], v[146:149], v[184:187], v[62:65]
	v_mfma_f32_16x16x32_bf16 v[58:61], v[154:157], v[184:187], v[58:61]
	v_mfma_f32_16x16x32_bf16 v[54:57], v[146:149], v[196:199], v[54:57]
	v_mfma_f32_16x16x32_bf16 v[50:53], v[154:157], v[196:199], v[50:53]
	v_mfma_f32_16x16x32_bf16 v[38:41], v[146:149], v[204:207], v[38:41]
	v_mfma_f32_16x16x32_bf16 v[34:37], v[154:157], v[204:207], v[34:37]
	v_mfma_f32_16x16x32_bf16 v[22:25], v[146:149], v[212:215], v[22:25]
	v_mfma_f32_16x16x32_bf16 v[18:21], v[154:157], v[212:215], v[18:21]
	v_mfma_f32_16x16x32_bf16 v[46:49], v[162:165], v[180:183], v[46:49]
	v_mfma_f32_16x16x32_bf16 v[42:45], v[170:173], v[180:183], v[42:45]
	v_mfma_f32_16x16x32_bf16 v[30:33], v[162:165], v[188:191], v[30:33]
	v_mfma_f32_16x16x32_bf16 v[26:29], v[170:173], v[188:191], v[26:29]
	v_mfma_f32_16x16x32_bf16 v[14:17], v[162:165], v[200:203], v[14:17]
	v_mfma_f32_16x16x32_bf16 v[10:13], v[170:173], v[200:203], v[10:13]
	v_mfma_f32_16x16x32_bf16 v[6:9], v[162:165], v[208:211], v[6:9]
	v_mfma_f32_16x16x32_bf16 v[2:5], v[170:173], v[208:211], v[2:5]
	v_mfma_f32_16x16x32_bf16 v[46:49], v[166:169], v[184:187], v[46:49]
	v_mfma_f32_16x16x32_bf16 v[42:45], v[176:179], v[184:187], v[42:45]
	v_mfma_f32_16x16x32_bf16 v[30:33], v[166:169], v[196:199], v[30:33]
	v_mfma_f32_16x16x32_bf16 v[26:29], v[176:179], v[196:199], v[26:29]
	v_mfma_f32_16x16x32_bf16 v[14:17], v[166:169], v[204:207], v[14:17]
	v_mfma_f32_16x16x32_bf16 v[10:13], v[176:179], v[204:207], v[10:13]
	v_mfma_f32_16x16x32_bf16 v[6:9], v[166:169], v[212:215], v[6:9]
	v_mfma_f32_16x16x32_bf16 v[2:5], v[176:179], v[212:215], v[2:5]
	s_barrier
	s_add_i32 s56, s56, 2
	s_add_u32 s76, s76, 0x100
	s_addc_u32 s77, s77, 0
	s_add_u32 s34, s34, 0x100
	s_addc_u32 s35, s35, 0
	s_cmp_gt_u32 s56, 13
	s_cbranch_scc0 .LBB0_201
	s_and_b64 vcc, exec, s[66:67]
	s_cbranch_vccz .LBB0_204
	s_barrier
